# v054 + global attention softmax stabilised with a launch-wide upper bound c on the scores (Cauchy-Schwarz from q/k RMSNorm gains) when c<48: loop without per-tile row max/rescale check; online-max loo
# speedup vs baseline: 1.0041x; 1.0041x over previous
.Lattn_fx_top:
	s_add_i32 s11, s10, -1
	s_min_i32 s1, s11, s58
	s_lshl_b32 s44, s1, 6
	s_ashr_i32 s45, s44, 31
	v_mad_i64_i32 v[200:201], s[46:47], s1, v239, v[194:195]
	v_lshl_add_u64 v[236:237], s[44:45], 1, v[208:209]
	s_mov_b32 s12, s3
	s_mov_b32 s3, s0
	s_add_i32 s15, s12, 0
	s_add_i32 s24, s10, -2
	s_cmp_lt_u32 s24, s16
	s_cselect_b64 s[0:1], -1, 0
	s_add_i32 s23, s3, 0
	s_waitcnt lgkmcnt(0)
	s_barrier
	v_add_u32_e32 v252, s15, v193
	ds_read_b128 v[162:165], v252
	ds_read_b128 v[178:181], v252 offset:4608
	ds_read_b128 v[166:169], v252 offset:32
	ds_read_b128 v[182:185], v252 offset:4640
	ds_read_b128 v[170:173], v252 offset:64
	ds_read_b128 v[186:189], v252 offset:4672
	ds_read_b128 v[174:177], v252 offset:96
	ds_read_b128 v[82:85], v252 offset:4704
	global_load_dwordx4 v[154:157], v[200:201], off offset:1024
	global_load_dwordx4 v[158:161], v[236:237], off
	v_add_u32_e32 v253, s23, v0
	v_exp_f32_e32 v66, v66
	v_exp_f32_e32 v67, v67
	v_exp_f32_e32 v68, v68
	v_exp_f32_e32 v69, v69
	v_add_f32_e32 v246, v66, v67
	v_cvt_pk_bf16_f32 v66, v66, v67
	s_waitcnt lgkmcnt(7)
	v_mfma_f32_32x32x16_bf16 v[114:129], v[162:165], v[130:133], v[50:65]
	ds_read_b128 v[86:89], v253 offset:9216
	ds_read_b128 v[216:219], v253 offset:13824
	v_exp_f32_e32 v70, v70
	v_exp_f32_e32 v71, v71
	v_add_f32_e32 v246, v68, v246
	v_add_f32_e32 v246, v69, v246
	v_cvt_pk_bf16_f32 v67, v68, v69
	s_waitcnt lgkmcnt(8)
	v_mfma_f32_32x32x16_bf16 v[98:113], v[178:181], v[130:133], v[50:65]
	ds_read_b128 v[90:93], v253 offset:9248
	ds_read_b128 v[220:223], v253 offset:13856
	v_exp_f32_e32 v72, v72
	v_exp_f32_e32 v73, v73
	v_add_f32_e32 v246, v70, v246
	v_add_f32_e32 v246, v71, v246
	v_cvt_pk_bf16_f32 v68, v70, v71
	s_waitcnt lgkmcnt(9)
	v_mfma_f32_32x32x16_bf16 v[114:129], v[166:169], v[134:137], v[114:129]
	ds_read_b128 v[94:97], v253 offset:9280
	ds_read_b128 v[224:227], v253 offset:13888
	v_exp_f32_e32 v74, v74
	v_exp_f32_e32 v75, v75
	v_add_f32_e32 v246, v72, v246
	v_add_f32_e32 v246, v73, v246
	v_cvt_pk_bf16_f32 v69, v72, v73
	s_waitcnt lgkmcnt(10)
	v_mfma_f32_32x32x16_bf16 v[98:113], v[182:185], v[134:137], v[98:113]
	ds_read_b128 v[212:215], v253 offset:9312
	ds_read_b128 v[242:245], v253 offset:13920
	v_exp_f32_e32 v76, v76
	v_exp_f32_e32 v77, v77
	v_add_f32_e32 v246, v74, v246
	v_add_f32_e32 v246, v75, v246
	v_cvt_pk_bf16_f32 v70, v74, v75
	s_waitcnt lgkmcnt(11)
	v_mfma_f32_32x32x16_bf16 v[114:129], v[170:173], v[138:141], v[114:129]
	v_exp_f32_e32 v78, v78
	v_exp_f32_e32 v79, v79
	v_add_f32_e32 v246, v76, v246
	v_add_f32_e32 v246, v77, v246
	v_cvt_pk_bf16_f32 v71, v76, v77
	s_waitcnt lgkmcnt(10)
	v_mfma_f32_32x32x16_bf16 v[98:113], v[186:189], v[138:141], v[98:113]
	v_exp_f32_e32 v80, v80
	v_exp_f32_e32 v81, v81
	v_add_f32_e32 v246, v78, v246
	v_add_f32_e32 v246, v79, v246
	v_cvt_pk_bf16_f32 v72, v78, v79
	s_waitcnt lgkmcnt(9)
	v_mfma_f32_32x32x16_bf16 v[114:129], v[174:177], v[142:145], v[114:129]
	v_exp_f32_e32 v34, v34
	v_exp_f32_e32 v35, v35
	v_add_f32_e32 v246, v80, v246
	v_add_f32_e32 v246, v81, v246
	v_cvt_pk_bf16_f32 v73, v80, v81
	s_waitcnt lgkmcnt(8)
	v_mfma_f32_32x32x16_bf16 v[98:113], v[82:85], v[142:145], v[98:113]
	v_exp_f32_e32 v36, v36
	v_exp_f32_e32 v37, v37
	v_add_f32_e32 v247, v34, v35
	v_cvt_pk_bf16_f32 v74, v34, v35
	s_waitcnt lgkmcnt(7)
	v_mfma_f32_32x32x16_bf16 v[18:33], v[86:89], v[66:69], v[18:33]
	v_exp_f32_e32 v38, v38
	v_exp_f32_e32 v39, v39
	v_add_f32_e32 v247, v36, v247
	v_add_f32_e32 v247, v37, v247
	v_cvt_pk_bf16_f32 v75, v36, v37
	s_waitcnt lgkmcnt(6)
	v_mfma_f32_32x32x16_bf16 v[2:17], v[216:219], v[66:69], v[2:17]
	v_exp_f32_e32 v40, v40
	v_exp_f32_e32 v41, v41
	v_add_f32_e32 v247, v38, v247
	v_add_f32_e32 v247, v39, v247
	v_cvt_pk_bf16_f32 v76, v38, v39
	s_waitcnt lgkmcnt(5)
	v_mfma_f32_32x32x16_bf16 v[18:33], v[90:93], v[70:73], v[18:33]
	v_exp_f32_e32 v42, v42
	v_exp_f32_e32 v43, v43
	v_add_f32_e32 v247, v40, v247
	v_add_f32_e32 v247, v41, v247
	v_cvt_pk_bf16_f32 v77, v40, v41
	s_waitcnt lgkmcnt(4)
	v_mfma_f32_32x32x16_bf16 v[2:17], v[220:223], v[70:73], v[2:17]
	v_exp_f32_e32 v44, v44
	v_exp_f32_e32 v45, v45
	v_add_f32_e32 v247, v42, v247
	v_add_f32_e32 v247, v43, v247
	v_cvt_pk_bf16_f32 v78, v42, v43
	s_waitcnt lgkmcnt(3)
	v_mfma_f32_32x32x16_bf16 v[18:33], v[94:97], v[74:77], v[18:33]
	v_exp_f32_e32 v46, v46
	v_exp_f32_e32 v47, v47
	v_add_f32_e32 v247, v44, v247
	v_add_f32_e32 v247, v45, v247
	v_cvt_pk_bf16_f32 v79, v44, v45
	s_waitcnt lgkmcnt(2)
	v_mfma_f32_32x32x16_bf16 v[2:17], v[224:227], v[74:77], v[2:17]
	v_exp_f32_e32 v48, v48
	v_exp_f32_e32 v49, v49
	v_add_f32_e32 v247, v46, v247
	v_add_f32_e32 v247, v47, v247
	v_cvt_pk_bf16_f32 v80, v46, v47
	v_cvt_pk_bf16_f32 v81, v48, v49
	v_add_f32_e32 v247, v48, v247
	v_add_f32_e32 v247, v49, v247
	s_waitcnt lgkmcnt(1)
	v_mfma_f32_32x32x16_bf16 v[18:33], v[212:215], v[78:81], v[18:33]
	s_waitcnt lgkmcnt(0)
	v_mfma_f32_32x32x16_bf16 v[2:17], v[242:245], v[78:81], v[2:17]
	v_add_f32_e32 v210, v210, v246
	v_add_f32_e32 v210, v210, v247
	s_cmp_ge_u32 s24, s16
	s_cbranch_scc1 .Lattn_fx_skipw1
	s_add_i32 s24, s2, 0
	v_add_u32_e32 v200, s24, v192
	v_add_u32_e32 v201, s24, v204
	s_waitcnt vmcnt(3)
	ds_write_b128 v200, v[146:149]
	s_waitcnt vmcnt(2)
	ds_write_b128 v201, v[150:153] offset:9216
.Lattn_fx_skipw1:
	s_min_i32 s24, s10, s58
	s_lshl_b32 s44, s24, 6
	s_ashr_i32 s45, s44, 31
	v_mad_i64_i32 v[200:201], s[46:47], s24, v239, v[194:195]
	v_lshl_add_u64 v[236:237], s[44:45], 1, v[208:209]
	s_waitcnt lgkmcnt(0)
	s_barrier
	v_add_u32_e32 v252, s2, v205
	ds_read_b128 v[162:165], v252
	ds_read_b128 v[178:181], v252 offset:4608
	ds_read_b128 v[166:169], v252 offset:32
	ds_read_b128 v[182:185], v252 offset:4640
	ds_read_b128 v[170:173], v252 offset:64
	ds_read_b128 v[186:189], v252 offset:4672
	ds_read_b128 v[174:177], v252 offset:96
	ds_read_b128 v[82:85], v252 offset:4704
	global_load_dwordx4 v[146:149], v[200:201], off offset:1024
	global_load_dwordx4 v[150:153], v[236:237], off
	v_add_u32_e32 v253, s15, v0
	v_exp_f32_e32 v114, v114
	v_exp_f32_e32 v115, v115
	v_exp_f32_e32 v116, v116
	v_exp_f32_e32 v117, v117
	v_add_f32_e32 v246, v114, v115
	v_cvt_pk_bf16_f32 v114, v114, v115
	s_waitcnt lgkmcnt(7)
	v_mfma_f32_32x32x16_bf16 v[66:81], v[162:165], v[130:133], v[50:65]
	ds_read_b128 v[86:89], v253 offset:9216
	ds_read_b128 v[216:219], v253 offset:13824
	v_exp_f32_e32 v118, v118
	v_exp_f32_e32 v119, v119
	v_add_f32_e32 v246, v116, v246
	v_add_f32_e32 v246, v117, v246
	v_cvt_pk_bf16_f32 v115, v116, v117
	s_waitcnt lgkmcnt(8)
	v_mfma_f32_32x32x16_bf16 v[34:49], v[178:181], v[130:133], v[50:65]
	ds_read_b128 v[90:93], v253 offset:9248
	ds_read_b128 v[220:223], v253 offset:13856
	v_exp_f32_e32 v120, v120
	v_exp_f32_e32 v121, v121
	v_add_f32_e32 v246, v118, v246
	v_add_f32_e32 v246, v119, v246
	v_cvt_pk_bf16_f32 v116, v118, v119
	s_waitcnt lgkmcnt(9)
	v_mfma_f32_32x32x16_bf16 v[66:81], v[166:169], v[134:137], v[66:81]
	ds_read_b128 v[94:97], v253 offset:9280
	ds_read_b128 v[224:227], v253 offset:13888
	v_exp_f32_e32 v122, v122
	v_exp_f32_e32 v123, v123
	v_add_f32_e32 v246, v120, v246
	v_add_f32_e32 v246, v121, v246
	v_cvt_pk_bf16_f32 v117, v120, v121
	s_waitcnt lgkmcnt(10)
	v_mfma_f32_32x32x16_bf16 v[34:49], v[182:185], v[134:137], v[34:49]
	ds_read_b128 v[212:215], v253 offset:9312
	ds_read_b128 v[242:245], v253 offset:13920
	v_exp_f32_e32 v124, v124
	v_exp_f32_e32 v125, v125
	v_add_f32_e32 v246, v122, v246
	v_add_f32_e32 v246, v123, v246
	v_cvt_pk_bf16_f32 v118, v122, v123
	s_waitcnt lgkmcnt(11)
	v_mfma_f32_32x32x16_bf16 v[66:81], v[170:173], v[138:141], v[66:81]
	v_exp_f32_e32 v126, v126
	v_exp_f32_e32 v127, v127
	v_add_f32_e32 v246, v124, v246
	v_add_f32_e32 v246, v125, v246
	v_cvt_pk_bf16_f32 v119, v124, v125
	s_waitcnt lgkmcnt(10)
	v_mfma_f32_32x32x16_bf16 v[34:49], v[186:189], v[138:141], v[34:49]
	v_exp_f32_e32 v128, v128
	v_exp_f32_e32 v129, v129
	v_add_f32_e32 v246, v126, v246
	v_add_f32_e32 v246, v127, v246
	v_cvt_pk_bf16_f32 v120, v126, v127
	s_waitcnt lgkmcnt(9)
	v_mfma_f32_32x32x16_bf16 v[66:81], v[174:177], v[142:145], v[66:81]
	v_exp_f32_e32 v98, v98
	v_exp_f32_e32 v99, v99
	v_add_f32_e32 v246, v128, v246
	v_add_f32_e32 v246, v129, v246
	v_cvt_pk_bf16_f32 v121, v128, v129
	s_waitcnt lgkmcnt(8)
	v_mfma_f32_32x32x16_bf16 v[34:49], v[82:85], v[142:145], v[34:49]
	v_exp_f32_e32 v100, v100
	v_exp_f32_e32 v101, v101
	v_add_f32_e32 v247, v98, v99
	v_cvt_pk_bf16_f32 v122, v98, v99
	s_waitcnt lgkmcnt(7)
	v_mfma_f32_32x32x16_bf16 v[18:33], v[86:89], v[114:117], v[18:33]
	v_exp_f32_e32 v102, v102
	v_exp_f32_e32 v103, v103
	v_add_f32_e32 v247, v100, v247
	v_add_f32_e32 v247, v101, v247
	v_cvt_pk_bf16_f32 v123, v100, v101
	s_waitcnt lgkmcnt(6)
	v_mfma_f32_32x32x16_bf16 v[2:17], v[216:219], v[114:117], v[2:17]
	v_exp_f32_e32 v104, v104
	v_exp_f32_e32 v105, v105
	v_add_f32_e32 v247, v102, v247
	v_add_f32_e32 v247, v103, v247
	v_cvt_pk_bf16_f32 v124, v102, v103
	s_waitcnt lgkmcnt(5)
	v_mfma_f32_32x32x16_bf16 v[18:33], v[90:93], v[118:121], v[18:33]
	v_exp_f32_e32 v106, v106
	v_exp_f32_e32 v107, v107
	v_add_f32_e32 v247, v104, v247
	v_add_f32_e32 v247, v105, v247
	v_cvt_pk_bf16_f32 v125, v104, v105
	s_waitcnt lgkmcnt(4)
	v_mfma_f32_32x32x16_bf16 v[2:17], v[220:223], v[118:121], v[2:17]
	v_exp_f32_e32 v108, v108
	v_exp_f32_e32 v109, v109
	v_add_f32_e32 v247, v106, v247
	v_add_f32_e32 v247, v107, v247
	v_cvt_pk_bf16_f32 v126, v106, v107
	s_waitcnt lgkmcnt(3)
	v_mfma_f32_32x32x16_bf16 v[18:33], v[94:97], v[122:125], v[18:33]
	v_exp_f32_e32 v110, v110
	v_exp_f32_e32 v111, v111
	v_add_f32_e32 v247, v108, v247
	v_add_f32_e32 v247, v109, v247
	v_cvt_pk_bf16_f32 v127, v108, v109
	s_waitcnt lgkmcnt(2)
	v_mfma_f32_32x32x16_bf16 v[2:17], v[224:227], v[122:125], v[2:17]
	v_exp_f32_e32 v112, v112
	v_exp_f32_e32 v113, v113
	v_add_f32_e32 v247, v110, v247
	v_add_f32_e32 v247, v111, v247
	v_cvt_pk_bf16_f32 v128, v110, v111
	v_cvt_pk_bf16_f32 v129, v112, v113
	v_add_f32_e32 v247, v112, v247
	v_add_f32_e32 v247, v113, v247
	s_waitcnt lgkmcnt(1)
	v_mfma_f32_32x32x16_bf16 v[18:33], v[212:215], v[126:129], v[18:33]
	s_waitcnt lgkmcnt(0)
	v_mfma_f32_32x32x16_bf16 v[2:17], v[242:245], v[126:129], v[2:17]
	v_add_f32_e32 v210, v210, v246
	v_add_f32_e32 v210, v210, v247
	s_cmp_ge_u32 s11, s16
	s_cbranch_scc1 .Lattn_fx_skipw2
	v_add_u32_e32 v200, s23, v192
	v_add_u32_e32 v201, s23, v204
	s_waitcnt vmcnt(3)
	ds_write_b128 v200, v[154:157]
	s_waitcnt vmcnt(2)
	ds_write_b128 v201, v[158:161] offset:9216
